# o_gla phase: state fragment loads issued together, gla_norm_g loaded once, per-pass waits on LDS only
# baseline (speedup 1.0000x reference)
; DI void phase_ogla(const Params& p, char* lds, int l) {
;     ...
;   for (int it = blockIdx.x; it < BATCH * NCH; it += gridDim.x) {
;     const int b = it >> 8, c = it & 255;
;     const size_t row = (size_t)b * SEQ + c * 64 + tb * 32 + r;
;     bf16x8 qf[4];
; #pragma unroll
;     for (int ks = 0; ks < 4; ++ks) qf[ks] = *(const bf16x8*)(qs + row * 256 + hh * 64 + ks * 16 + h * 8);
;     uint2 zq[16];
;     {
;       const size_t rowz = (size_t)b * SEQ + c * 64 + tb * 32;
; #pragma unroll
;       for (int it2 = 0; it2 < 16; ++it2) { const int id = it2 * 64 + lane; zq[it2] = *(const uint2*)(proj + (rowz + (id >> 5)) * NP + C_GZ + hh * 128 + (id & 31) * 4); }
;     }
.LBB0_743:
	s_ashr_i32 s10, s17, 8
	s_ashr_i32 s11, s10, 31
	s_lshl_b64 s[10:11], s[10:11], 14
	s_and_b32 s9, s16, 0x3fc0
	s_or_b32 s10, s10, s9
	s_or_b64 s[12:13], s[10:11], s[76:77]
	v_mov_b32_e32 v1, s13
	v_or_b32_e32 v0, s12, v78
	v_lshlrev_b64 v[0:1], 9, v[0:1]
	v_lshl_add_u64 v[0:1], v[80:81], 0, v[0:1]
	global_load_dwordx4 v[48:51], v[0:1], off
	global_load_dwordx4 v[72:75], v[0:1], off offset:32
	global_load_dwordx4 v[68:71], v[0:1], off offset:64
	global_load_dwordx4 v[64:67], v[0:1], off offset:96
	v_or_b32_e32 v184, s12, v76
	v_mov_b64_e32 v[0:1], s[30:31]
	v_mad_u64_u32 v[2:3], s[18:19], v184, s0, v[0:1]
	v_mad_i32_i24 v3, s11, v247, v3
	v_lshl_add_u64 v[2:3], v[2:3], 0, s[6:7]
	v_lshl_add_u64 v[2:3], v[2:3], 0, v[196:197]
	v_add_co_u32_e32 v2, vcc, s48, v2
	v_or_b32_e32 v180, s12, v88
	s_nop 0
	v_addc_co_u32_e32 v3, vcc, 0, v3, vcc
	global_load_dwordx2 v[188:189], v[2:3], off offset:2304
	v_mad_u64_u32 v[2:3], s[18:19], v180, s0, v[0:1]
	v_mad_i32_i24 v3, s11, v247, v3
	v_lshl_add_u64 v[2:3], v[2:3], 0, s[6:7]
	v_lshl_add_u64 v[2:3], v[2:3], 0, v[196:197]
	v_add_co_u32_e32 v2, vcc, s48, v2
	v_or_b32_e32 v176, s12, v90
	s_nop 0
	v_addc_co_u32_e32 v3, vcc, 0, v3, vcc
	global_load_dwordx2 v[186:187], v[2:3], off offset:2304
	v_mad_u64_u32 v[2:3], s[18:19], v176, s0, v[0:1]
	v_mad_i32_i24 v3, s11, v247, v3
	v_lshl_add_u64 v[2:3], v[2:3], 0, s[6:7]
	v_lshl_add_u64 v[2:3], v[2:3], 0, v[196:197]
	v_add_co_u32_e32 v2, vcc, s48, v2
	v_or_b32_e32 v172, s12, v92
	s_nop 0
	v_addc_co_u32_e32 v3, vcc, 0, v3, vcc
	global_load_dwordx2 v[182:183], v[2:3], off offset:2304
	v_mad_u64_u32 v[2:3], s[18:19], v172, s0, v[0:1]
	v_mad_i32_i24 v3, s11, v247, v3
	v_lshl_add_u64 v[2:3], v[2:3], 0, s[6:7]
	v_lshl_add_u64 v[2:3], v[2:3], 0, v[196:197]
	v_add_co_u32_e32 v2, vcc, s48, v2
	v_or_b32_e32 v168, s12, v94
	s_nop 0
	v_addc_co_u32_e32 v3, vcc, 0, v3, vcc
	global_load_dwordx2 v[178:179], v[2:3], off offset:2304
	v_mad_u64_u32 v[2:3], s[18:19], v168, s0, v[0:1]
	v_mad_i32_i24 v3, s11, v247, v3
	v_lshl_add_u64 v[2:3], v[2:3], 0, s[6:7]
	v_lshl_add_u64 v[2:3], v[2:3], 0, v[196:197]
	v_add_co_u32_e32 v2, vcc, s48, v2
	v_or_b32_e32 v164, s12, v96
	s_nop 0
	v_addc_co_u32_e32 v3, vcc, 0, v3, vcc
	global_load_dwordx2 v[174:175], v[2:3], off offset:2304
	v_mad_u64_u32 v[2:3], s[18:19], v164, s0, v[0:1]
	v_mad_i32_i24 v3, s11, v247, v3
	v_lshl_add_u64 v[2:3], v[2:3], 0, s[6:7]
	v_lshl_add_u64 v[2:3], v[2:3], 0, v[196:197]
	v_add_co_u32_e32 v2, vcc, s48, v2
	v_or_b32_e32 v160, s12, v98
	s_nop 0
	v_addc_co_u32_e32 v3, vcc, 0, v3, vcc
	global_load_dwordx2 v[170:171], v[2:3], off offset:2304
	v_mad_u64_u32 v[2:3], s[18:19], v160, s0, v[0:1]
	v_mad_i32_i24 v3, s11, v247, v3
	v_lshl_add_u64 v[2:3], v[2:3], 0, s[6:7]
	v_lshl_add_u64 v[2:3], v[2:3], 0, v[196:197]
	v_add_co_u32_e32 v2, vcc, s48, v2
	v_or_b32_e32 v156, s12, v100
	s_nop 0
	v_addc_co_u32_e32 v3, vcc, 0, v3, vcc
	global_load_dwordx2 v[166:167], v[2:3], off offset:2304
	v_mad_u64_u32 v[2:3], s[18:19], v156, s0, v[0:1]
	v_mad_i32_i24 v3, s11, v247, v3
	v_lshl_add_u64 v[2:3], v[2:3], 0, s[6:7]
	v_lshl_add_u64 v[2:3], v[2:3], 0, v[196:197]
	v_add_co_u32_e32 v2, vcc, s48, v2
	v_or_b32_e32 v154, s12, v102
	s_nop 0
	v_addc_co_u32_e32 v3, vcc, 0, v3, vcc
	global_load_dwordx2 v[162:163], v[2:3], off offset:2304
	v_mad_u64_u32 v[2:3], s[18:19], v154, s0, v[0:1]
	v_mad_i32_i24 v3, s11, v247, v3
	v_lshl_add_u64 v[2:3], v[2:3], 0, s[6:7]
	v_lshl_add_u64 v[2:3], v[2:3], 0, v[196:197]
	v_add_co_u32_e32 v2, vcc, s48, v2
	v_or_b32_e32 v150, s12, v104
	s_nop 0
	v_addc_co_u32_e32 v3, vcc, 0, v3, vcc
	global_load_dwordx2 v[158:159], v[2:3], off offset:2304
	v_mad_u64_u32 v[2:3], s[18:19], v150, s0, v[0:1]
	v_mad_i32_i24 v3, s11, v247, v3
	v_lshl_add_u64 v[2:3], v[2:3], 0, s[6:7]
	v_lshl_add_u64 v[2:3], v[2:3], 0, v[196:197]
	v_add_co_u32_e32 v2, vcc, s48, v2
	v_or_b32_e32 v146, s12, v106
	s_nop 0
	v_addc_co_u32_e32 v3, vcc, 0, v3, vcc
	global_load_dwordx2 v[152:153], v[2:3], off offset:2304
	v_mad_u64_u32 v[2:3], s[18:19], v146, s0, v[0:1]
	v_mad_i32_i24 v3, s11, v247, v3
	v_lshl_add_u64 v[2:3], v[2:3], 0, s[6:7]
	v_lshl_add_u64 v[2:3], v[2:3], 0, v[196:197]
	v_add_co_u32_e32 v2, vcc, s48, v2
	v_or_b32_e32 v142, s12, v108
	s_nop 0
	v_addc_co_u32_e32 v3, vcc, 0, v3, vcc
	global_load_dwordx2 v[148:149], v[2:3], off offset:2304
	v_mad_u64_u32 v[2:3], s[18:19], v142, s0, v[0:1]
	v_mad_i32_i24 v3, s11, v247, v3
	v_lshl_add_u64 v[2:3], v[2:3], 0, s[6:7]
	v_lshl_add_u64 v[2:3], v[2:3], 0, v[196:197]
	v_add_co_u32_e32 v2, vcc, s48, v2
	v_or_b32_e32 v138, s12, v110
	s_nop 0
	v_addc_co_u32_e32 v3, vcc, 0, v3, vcc
	global_load_dwordx2 v[144:145], v[2:3], off offset:2304
	v_mad_u64_u32 v[2:3], s[18:19], v138, s0, v[0:1]
	v_mad_i32_i24 v3, s11, v247, v3
	v_lshl_add_u64 v[2:3], v[2:3], 0, s[6:7]
	v_lshl_add_u64 v[2:3], v[2:3], 0, v[196:197]
	v_add_co_u32_e32 v2, vcc, s48, v2
	v_or_b32_e32 v134, s12, v112
	s_nop 0
	v_addc_co_u32_e32 v3, vcc, 0, v3, vcc
	global_load_dwordx2 v[140:141], v[2:3], off offset:2304
	v_mad_u64_u32 v[2:3], s[18:19], v134, s0, v[0:1]
	v_mad_i32_i24 v3, s11, v247, v3
	v_lshl_add_u64 v[2:3], v[2:3], 0, s[6:7]
	v_lshl_add_u64 v[2:3], v[2:3], 0, v[196:197]
	v_add_co_u32_e32 v2, vcc, s48, v2
	v_or_b32_e32 v130, s12, v114
	s_nop 0
	v_addc_co_u32_e32 v3, vcc, 0, v3, vcc
	global_load_dwordx2 v[136:137], v[2:3], off offset:2304
	v_mad_u64_u32 v[2:3], s[18:19], v130, s0, v[0:1]
	v_mad_i32_i24 v3, s11, v247, v3
	v_or_b32_e32 v126, s12, v116
	v_mov_b32_e32 v185, s13
	v_mov_b32_e32 v181, s13
	v_mov_b32_e32 v177, s13
	v_mov_b32_e32 v173, s13
	v_mov_b32_e32 v169, s13
	v_mov_b32_e32 v165, s13
	v_mov_b32_e32 v161, s13
; #define MFMA32(a, b, c) __builtin_amdgcn_mfma_f32_32x32x16_bf16((a), (b), (c), 0, 0, 0)
; DI void phase_ogla(const Params& p, char* lds, int l) {
;     ...
; #pragma unroll
;     for (int ks = 0; ks < 4; ++ks)
; #pragma unroll
;       for (int d = 0; d < 4; ++d) {
;         const bf16x8 sf = *(const bf16x8*)(sp + (d * 32 + r) * 64 + ks * 16 + h * 8);
;         O[d] = MFMA32(sf, qf[ks], O[d]);
;       }
;     float ss = 0.f;
; #pragma unroll
;     for (int d = 0; d < 4; ++d)
; #pragma unroll
;       for (int e = 0; e < 16; ++e) ss += O[d][e] * O[d][e];
;     ss += __shfl_xor(ss, 32);
	v_mov_b32_e32 v157, s13
	v_mov_b32_e32 v155, s13
	v_mov_b32_e32 v151, s13
	v_mov_b32_e32 v147, s13
	v_mov_b32_e32 v143, s13
	v_mov_b32_e32 v139, s13
	v_mov_b32_e32 v135, s13
	v_mov_b32_e32 v131, s13
	v_lshl_add_u64 v[2:3], v[2:3], 0, s[6:7]
	v_mov_b32_e32 v127, s13
	v_mad_u64_u32 v[0:1], s[12:13], v126, s0, v[0:1]
	v_lshl_add_u64 v[2:3], v[2:3], 0, v[196:197]
	v_mad_i32_i24 v1, s11, v247, v1
	v_add_co_u32_e32 v2, vcc, s48, v2
	v_lshl_add_u64 v[0:1], v[0:1], 0, s[6:7]
	s_ashr_i32 s9, s8, 31
	v_addc_co_u32_e32 v3, vcc, 0, v3, vcc
	v_lshl_add_u64 v[0:1], v[0:1], 0, v[196:197]
	s_lshl_b64 s[10:11], s[8:9], 14
	v_add_co_u32_e32 v0, vcc, s48, v0
	v_lshl_add_u64 v[200:201], v[82:83], 0, s[10:11]
	v_mov_b32_e32 v119, v197
	v_addc_co_u32_e32 v1, vcc, 0, v1, vcc
	v_lshl_add_u64 v[190:191], v[200:201], 0, v[118:119]
	global_load_dwordx2 v[132:133], v[2:3], off offset:2304
	global_load_dwordx2 v[128:129], v[0:1], off offset:2304
	global_load_dwordx4 v[192:195], v[190:191], off offset:32
	v_mov_b32_e32 v125, v197
	global_load_dwordx4 v[0:3], v[190:191], off
	v_mov_b32_e32 v121, v197
	v_mov_b32_e32 v123, v197
	v_mov_b32_e32 v125, v197
	v_lshl_add_u64 v[232:233], v[200:201], 0, v[120:121]
	v_lshl_add_u64 v[236:237], v[200:201], 0, v[122:123]
	v_lshl_add_u64 v[244:245], v[200:201], 0, v[124:125]
	global_load_dwordx4 v[16:19], v[232:233], off
	global_load_dwordx4 v[204:207], v[232:233], off offset:32
	global_load_dwordx4 v[32:35], v[236:237], off
	global_load_dwordx4 v[208:211], v[236:237], off offset:32
	global_load_dwordx4 v[52:55], v[244:245], off
	global_load_dwordx4 v[212:215], v[244:245], off offset:32
	global_load_dwordx4 v[216:219], v[190:191], off offset:64
	global_load_dwordx4 v[220:223], v[232:233], off offset:64
	global_load_dwordx4 v[224:227], v[236:237], off offset:64
	global_load_dwordx4 v[228:231], v[244:245], off offset:64
	global_load_dwordx4 v[240:243], v[190:191], off offset:96
	global_load_dwordx4 v[248:251], v[232:233], off offset:96
	v_mov_b32_e32 v121, v197
	s_nop 0
	s_nop 0
	s_nop 0
	s_waitcnt vmcnt(12)
	v_mfma_f32_32x32x16_bf16 v[0:15], v[0:3], v[48:51], 0
	s_nop 0
	s_nop 0
	v_mov_b32_e32 v123, v197
	s_nop 0
	s_nop 0
	s_mov_b64 s[10:11], 0x60
	s_add_i32 s17, s17, s34
	v_mfma_f32_32x32x16_bf16 v[0:15], v[192:195], v[72:75], v[0:15]
	s_nop 0
	s_nop 0
	s_add_i32 s8, s8, s21
	s_add_i32 s16, s16, s20
	s_cmpk_lt_i32 s17, 0x200
	s_waitcnt vmcnt(11)
	v_mfma_f32_32x32x16_bf16 v[16:31], v[16:19], v[48:51], 0
	s_waitcnt vmcnt(10)
	v_mfma_f32_32x32x16_bf16 v[16:31], v[204:207], v[72:75], v[16:31]
	global_load_dwordx4 v[204:207], v[236:237], off offset:96
	s_nop 0
	s_nop 0
	s_waitcnt vmcnt(10)
	v_mfma_f32_32x32x16_bf16 v[32:47], v[32:35], v[48:51], 0
	s_waitcnt vmcnt(9)
	v_mfma_f32_32x32x16_bf16 v[32:47], v[208:211], v[72:75], v[32:47]
	global_load_dwordx4 v[208:211], v[244:245], off offset:96
	s_nop 0
	s_nop 0
	s_waitcnt vmcnt(9)
	v_mfma_f32_32x32x16_bf16 v[48:63], v[52:55], v[48:51], 0
	s_waitcnt vmcnt(8)
	v_mfma_f32_32x32x16_bf16 v[48:63], v[212:215], v[72:75], v[48:63]
	s_nop 0
	s_nop 0
	s_waitcnt vmcnt(7)
	v_mfma_f32_32x32x16_bf16 v[0:15], v[216:219], v[68:71], v[0:15]
	s_nop 0
	s_nop 0
	s_waitcnt vmcnt(6)
	v_mfma_f32_32x32x16_bf16 v[16:31], v[220:223], v[68:71], v[16:31]
	s_nop 0
	s_nop 0
	s_waitcnt vmcnt(5)
	v_mfma_f32_32x32x16_bf16 v[32:47], v[224:227], v[68:71], v[32:47]
	s_nop 0
	s_nop 0
	s_waitcnt vmcnt(4)
	v_mfma_f32_32x32x16_bf16 v[48:63], v[228:231], v[68:71], v[48:63]
	s_nop 0
	s_nop 0
	s_waitcnt vmcnt(3)
	v_mfma_f32_32x32x16_bf16 v[0:15], v[240:243], v[64:67], v[0:15]
	s_nop 0
	s_nop 0
	s_nop 9
	v_mul_f32_e32 v74, v1, v1
	s_waitcnt vmcnt(2)
	v_mfma_f32_32x32x16_bf16 v[16:31], v[248:251], v[64:67], v[16:31]
	s_nop 0
	s_nop 0
	v_fmac_f32_e32 v74, v0, v0
	v_fmac_f32_e32 v74, v2, v2
	v_fmac_f32_e32 v74, v3, v3
	v_fmac_f32_e32 v74, v4, v4
	v_fmac_f32_e32 v74, v5, v5
	s_waitcnt vmcnt(1)
	v_mfma_f32_32x32x16_bf16 v[32:47], v[204:207], v[64:67], v[32:47]
	s_nop 0
	s_nop 0
	v_fmac_f32_e32 v74, v6, v6
	v_fmac_f32_e32 v74, v7, v7
	v_fmac_f32_e32 v74, v8, v8
	v_fmac_f32_e32 v74, v9, v9
	v_fmac_f32_e32 v74, v10, v10
	v_fmac_f32_e32 v74, v11, v11
	v_fmac_f32_e32 v74, v12, v12
	v_fmac_f32_e32 v74, v13, v13
	v_fmac_f32_e32 v74, v14, v14
	v_fmac_f32_e32 v74, v15, v15
	v_fmac_f32_e32 v74, v16, v16
	v_fmac_f32_e32 v74, v17, v17
	v_fmac_f32_e32 v74, v18, v18
	v_fmac_f32_e32 v74, v19, v19
	v_fmac_f32_e32 v74, v20, v20
	v_fmac_f32_e32 v74, v21, v21
	v_fmac_f32_e32 v74, v22, v22
	v_fmac_f32_e32 v74, v23, v23
	v_fmac_f32_e32 v74, v24, v24
	v_fmac_f32_e32 v74, v25, v25
	v_fmac_f32_e32 v74, v26, v26
	v_fmac_f32_e32 v74, v27, v27
	v_fmac_f32_e32 v74, v28, v28
	v_fmac_f32_e32 v74, v29, v29
	v_fmac_f32_e32 v74, v30, v30
	v_fmac_f32_e32 v74, v31, v31
	v_fmac_f32_e32 v74, v32, v32
	v_fmac_f32_e32 v74, v33, v33
	v_fmac_f32_e32 v74, v34, v34
	v_fmac_f32_e32 v74, v35, v35
	v_fmac_f32_e32 v74, v36, v36
	v_fmac_f32_e32 v74, v37, v37
	v_fmac_f32_e32 v74, v38, v38
	v_fmac_f32_e32 v74, v39, v39
	s_waitcnt vmcnt(0)
	v_mfma_f32_32x32x16_bf16 v[48:63], v[208:211], v[64:67], v[48:63]
	v_fmac_f32_e32 v74, v40, v40
	v_fmac_f32_e32 v74, v41, v41
	v_fmac_f32_e32 v74, v42, v42
	v_fmac_f32_e32 v74, v43, v43
	v_fmac_f32_e32 v74, v44, v44
	v_fmac_f32_e32 v74, v45, v45
	v_fmac_f32_e32 v74, v46, v46
	v_fmac_f32_e32 v74, v47, v47
	s_nop 3
	v_fmac_f32_e32 v74, v48, v48
	v_fmac_f32_e32 v74, v49, v49
	v_fmac_f32_e32 v74, v50, v50
	v_fmac_f32_e32 v74, v51, v51
	v_fmac_f32_e32 v74, v52, v52
	v_fmac_f32_e32 v74, v53, v53
	v_pk_mul_f32 v[72:73], v[54:55], v[54:55]
	v_pk_mul_f32 v[70:71], v[56:57], v[56:57]
	v_add_f32_e32 v72, v72, v74
	v_add_f32_e32 v72, v73, v72
	v_add_f32_e32 v70, v70, v72
	v_pk_mul_f32 v[68:69], v[58:59], v[58:59]
	v_add_f32_e32 v70, v71, v70
	v_add_f32_e32 v68, v68, v70
	v_pk_mul_f32 v[66:67], v[60:61], v[60:61]
	v_add_f32_e32 v68, v69, v68
	v_add_f32_e32 v66, v66, v68
	v_pk_mul_f32 v[64:65], v[62:63], v[62:63]
	v_add_f32_e32 v66, v67, v66
	v_add_f32_e32 v64, v64, v66
	v_add_f32_e32 v64, v65, v64
	ds_bpermute_b32 v65, v77, v64
	s_waitcnt lgkmcnt(0)
; DI float bf2f(unsigned u) { return __uint_as_float(u << 16); }
; DI unsigned cvtpk(float lo, float hi) { f32x2_t v = {lo, hi}; bf16x2_t r = __builtin_convertvector(v, bf16x2_t); return __builtin_bit_cast(unsigned, r); }
; DI float silu_f(float x) { return x * __builtin_amdgcn_rcpf(1.f + __expf(-x)); }
; DI void phase_ogla(const Params& p, char* lds, int l) {
;     ...
;     ss += __shfl_xor(ss, 32);
;     const float rstd = rsqrtf(ss * (1.f / 128.f) + EPS);
;     char* stg = lds + wave * 16896;
;     asm volatile("s_waitcnt lgkmcnt(0)" ::: "memory");
; #pragma unroll
;     for (int d = 0; d < 4; ++d)
; #pragma unroll
;       for (int g = 0; g < 4; ++g) {
;         float4 o; o.x = O[d][4 * g] * rstd; o.y = O[d][4 * g + 1] * rstd; o.z = O[d][4 * g + 2] * rstd; o.w = O[d][4 * g + 3] * rstd;
;         *(float4*)(stg + r * 528 + (d * 32 + 8 * g + 4 * h) * 4) = o;
;       }
;     asm volatile("s_waitcnt lgkmcnt(0)" ::: "memory");
;     const size_t row0 = (size_t)b * SEQ + c * 64 + tb * 32;
; #pragma unroll
;     for (int it2 = 0; it2 < 16; ++it2) {
;       const int id = it2 * 64 + lane, rr = id >> 5, cc = id & 31;
;       const float4 v = *(const float4*)(stg + rr * 528 + cc * 16);
;       const uint2 zr = zq[it2];
;       const float4 gv = *(const float4*)(gg + cc * 4);
;       const float z0 = bf2f(zr.x & 0xffffu), z1 = __uint_as_float(zr.x & 0xffff0000u), z2 = bf2f(zr.y & 0xffffu), z3 = __uint_as_float(zr.y & 0xffff0000u);
;       uint2 o;
;       o.x = cvtpk(v.x * gv.x * silu_f(z0), v.y * gv.y * silu_f(z1));
;       o.y = cvtpk(v.z * gv.z * silu_f(z2), v.w * gv.w * silu_f(z3));
;       *(uint2*)(mix + (row0 + rr) * 1024 + hh * 128 + cc * 4) = o;
;     }
	s_waitcnt lgkmcnt(0)
	v_add_f32_e32 v64, v64, v65
	v_fmamk_f32 v64, v64, 0x3c000000, v198
	v_cmp_gt_f32_e32 vcc, s99, v64
	v_mul_f32_e32 v65, 0x4b800000, v64
	s_nop 0
	v_cndmask_b32_e32 v64, v64, v65, vcc
	v_rsq_f32_e32 v64, v64
	s_nop 0
	v_mul_f32_e32 v65, 0x45800000, v64
	v_cndmask_b32_e32 v64, v64, v65, vcc
	v_pk_mul_f32 v[0:1], v[0:1], v[64:65] op_sel_hi:[1,0]
	v_pk_mul_f32 v[2:3], v[2:3], v[64:65] op_sel_hi:[1,0]
	ds_write_b128 v79, v[0:3]
	v_pk_mul_f32 v[0:1], v[4:5], v[64:65] op_sel_hi:[1,0]
	v_pk_mul_f32 v[2:3], v[6:7], v[64:65] op_sel_hi:[1,0]
	ds_write_b128 v79, v[0:3] offset:32
	v_pk_mul_f32 v[0:1], v[8:9], v[64:65] op_sel_hi:[1,0]
	v_pk_mul_f32 v[2:3], v[10:11], v[64:65] op_sel_hi:[1,0]
	ds_write_b128 v79, v[0:3] offset:64
	v_pk_mul_f32 v[0:1], v[12:13], v[64:65] op_sel_hi:[1,0]
	v_pk_mul_f32 v[2:3], v[14:15], v[64:65] op_sel_hi:[1,0]
	ds_write_b128 v79, v[0:3] offset:96
	v_pk_mul_f32 v[0:1], v[16:17], v[64:65] op_sel_hi:[1,0]
	v_pk_mul_f32 v[2:3], v[18:19], v[64:65] op_sel_hi:[1,0]
	ds_write_b128 v79, v[0:3] offset:128
	v_pk_mul_f32 v[0:1], v[20:21], v[64:65] op_sel_hi:[1,0]
	v_pk_mul_f32 v[2:3], v[22:23], v[64:65] op_sel_hi:[1,0]
	ds_write_b128 v79, v[0:3] offset:160
	v_pk_mul_f32 v[0:1], v[24:25], v[64:65] op_sel_hi:[1,0]
	v_pk_mul_f32 v[2:3], v[26:27], v[64:65] op_sel_hi:[1,0]
	ds_write_b128 v79, v[0:3] offset:192
	v_pk_mul_f32 v[0:1], v[28:29], v[64:65] op_sel_hi:[1,0]
	v_pk_mul_f32 v[2:3], v[30:31], v[64:65] op_sel_hi:[1,0]
	ds_write_b128 v79, v[0:3] offset:224
	v_pk_mul_f32 v[0:1], v[32:33], v[64:65] op_sel_hi:[1,0]
	v_pk_mul_f32 v[2:3], v[34:35], v[64:65] op_sel_hi:[1,0]
	ds_write_b128 v79, v[0:3] offset:256
	v_pk_mul_f32 v[0:1], v[36:37], v[64:65] op_sel_hi:[1,0]
	v_pk_mul_f32 v[2:3], v[38:39], v[64:65] op_sel_hi:[1,0]
	ds_write_b128 v79, v[0:3] offset:288
	v_pk_mul_f32 v[0:1], v[40:41], v[64:65] op_sel_hi:[1,0]
	v_pk_mul_f32 v[2:3], v[42:43], v[64:65] op_sel_hi:[1,0]
	ds_write_b128 v79, v[0:3] offset:320
	v_pk_mul_f32 v[0:1], v[44:45], v[64:65] op_sel_hi:[1,0]
	v_pk_mul_f32 v[2:3], v[46:47], v[64:65] op_sel_hi:[1,0]
	ds_write_b128 v79, v[0:3] offset:352
	v_pk_mul_f32 v[0:1], v[48:49], v[64:65] op_sel_hi:[1,0]
	v_pk_mul_f32 v[2:3], v[50:51], v[64:65] op_sel_hi:[1,0]
	ds_write_b128 v79, v[0:3] offset:384
	v_pk_mul_f32 v[0:1], v[52:53], v[64:65] op_sel_hi:[1,0]
	v_pk_mul_f32 v[2:3], v[54:55], v[64:65] op_sel_hi:[1,0]
	ds_write_b128 v79, v[0:3] offset:416
	v_pk_mul_f32 v[0:1], v[56:57], v[64:65] op_sel_hi:[1,0]
	v_pk_mul_f32 v[2:3], v[58:59], v[64:65] op_sel_hi:[1,0]
	ds_write_b128 v79, v[0:3] offset:448
	v_pk_mul_f32 v[0:1], v[60:61], v[64:65] op_sel_hi:[1,0]
	v_pk_mul_f32 v[2:3], v[62:63], v[64:65] op_sel_hi:[1,0]
	ds_write_b128 v79, v[0:3] offset:480
	s_waitcnt lgkmcnt(0)
	global_load_dwordx4 v[210:213], v[84:85], off
	ds_read_b128 v[0:3], v89
	v_lshlrev_b32_e32 v8, 16, v188
	v_and_b32_e32 v9, 0xffff0000, v188
	v_lshlrev_b32_e32 v10, 16, v189
	v_and_b32_e32 v11, 0xffff0000, v189
	s_waitcnt vmcnt(0) lgkmcnt(0)
	v_mul_f32_e32 v0, v0, v210
	v_mul_f32_e32 v4, 0xbfb8aa3b, v8
	v_exp_f32_e32 v4, v4
	v_mul_f32_e32 v1, v1, v211
	v_add_f32_e32 v4, 1.0, v4
	v_rcp_f32_e32 v4, v4
	s_nop 0
	v_mul_f32_e32 v4, v4, v8
	v_mul_f32_e32 v0, v4, v0
	v_mul_f32_e32 v4, 0xbfb8aa3b, v9
	v_exp_f32_e32 v4, v4
	v_lshlrev_b32_e32 v8, 16, v186
	v_add_f32_e32 v4, 1.0, v4
	v_rcp_f32_e32 v4, v4
	s_nop 0
	v_mul_f32_e32 v4, v4, v9
	v_mul_f32_e32 v1, v4, v1
	v_cvt_pk_bf16_f32 v0, v0, v1
	v_mul_f32_e32 v1, v2, v212
	v_mul_f32_e32 v2, 0xbfb8aa3b, v10
	v_exp_f32_e32 v2, v2
	v_and_b32_e32 v9, 0xffff0000, v186
	v_add_f32_e32 v2, 1.0, v2
	v_rcp_f32_e32 v2, v2
	s_nop 0
	v_mul_f32_e32 v2, v2, v10
	v_mul_f32_e32 v1, v2, v1
	v_mul_f32_e32 v2, v3, v213
	v_mul_f32_e32 v3, 0xbfb8aa3b, v11
	v_exp_f32_e32 v3, v3
	v_lshlrev_b32_e32 v10, 16, v187
	v_add_f32_e32 v3, 1.0, v3
	v_rcp_f32_e32 v3, v3
	s_nop 0
	v_mul_f32_e32 v3, v3, v11
	v_mul_f32_e32 v2, v3, v2
	v_cvt_pk_bf16_f32 v1, v1, v2
	v_lshlrev_b64 v[2:3], 11, v[184:185]
	v_lshl_add_u64 v[2:3], v[86:87], 0, v[2:3]
	global_store_dwordx2 v[2:3], v[0:1], off
	ds_read_b128 v[0:3], v89 offset:1056
	v_and_b32_e32 v11, 0xffff0000, v187
	s_waitcnt lgkmcnt(0)
	v_mul_f32_e32 v0, v0, v210
	v_mul_f32_e32 v4, 0xbfb8aa3b, v8
	v_exp_f32_e32 v4, v4
	v_mul_f32_e32 v1, v1, v211
	v_add_f32_e32 v4, 1.0, v4
	v_rcp_f32_e32 v4, v4
	s_nop 0
	v_mul_f32_e32 v4, v4, v8
	v_mul_f32_e32 v0, v4, v0
	v_mul_f32_e32 v4, 0xbfb8aa3b, v9
	v_exp_f32_e32 v4, v4
	v_lshlrev_b32_e32 v8, 16, v182
	v_add_f32_e32 v4, 1.0, v4
	v_rcp_f32_e32 v4, v4
	s_nop 0
	v_mul_f32_e32 v4, v4, v9
	v_mul_f32_e32 v1, v4, v1
	v_cvt_pk_bf16_f32 v0, v0, v1
	v_mul_f32_e32 v1, v2, v212
	v_mul_f32_e32 v2, 0xbfb8aa3b, v10
	v_exp_f32_e32 v2, v2
	v_and_b32_e32 v9, 0xffff0000, v182
	v_add_f32_e32 v2, 1.0, v2
	v_rcp_f32_e32 v2, v2
	s_nop 0
	v_mul_f32_e32 v2, v2, v10
	v_mul_f32_e32 v1, v2, v1
	v_mul_f32_e32 v2, v3, v213
	v_mul_f32_e32 v3, 0xbfb8aa3b, v11
	v_exp_f32_e32 v3, v3
	v_lshlrev_b32_e32 v10, 16, v183
	v_add_f32_e32 v3, 1.0, v3
	v_rcp_f32_e32 v3, v3
	s_nop 0
	v_mul_f32_e32 v3, v3, v11
	v_mul_f32_e32 v2, v3, v2
	v_cvt_pk_bf16_f32 v1, v1, v2
	v_lshlrev_b64 v[2:3], 11, v[180:181]
	v_lshl_add_u64 v[2:3], v[86:87], 0, v[2:3]
	global_store_dwordx2 v[2:3], v[0:1], off
	ds_read_b128 v[0:3], v89 offset:2112
	v_and_b32_e32 v11, 0xffff0000, v183
	s_waitcnt lgkmcnt(0)
; DI float bf2f(unsigned u) { return __uint_as_float(u << 16); }
; DI unsigned cvtpk(float lo, float hi) { f32x2_t v = {lo, hi}; bf16x2_t r = __builtin_convertvector(v, bf16x2_t); return __builtin_bit_cast(unsigned, r); }
; DI float silu_f(float x) { return x * __builtin_amdgcn_rcpf(1.f + __expf(-x)); }
; DI void phase_ogla(const Params& p, char* lds, int l) {
;     ...
; #pragma unroll
;     for (int it2 = 0; it2 < 16; ++it2) {
;       const int id = it2 * 64 + lane, rr = id >> 5, cc = id & 31;
;       const float4 v = *(const float4*)(stg + rr * 528 + cc * 16);
;       const uint2 zr = zq[it2];
;       const float4 gv = *(const float4*)(gg + cc * 4);
;       const float z0 = bf2f(zr.x & 0xffffu), z1 = __uint_as_float(zr.x & 0xffff0000u), z2 = bf2f(zr.y & 0xffffu), z3 = __uint_as_float(zr.y & 0xffff0000u);
;       uint2 o;
;       o.x = cvtpk(v.x * gv.x * silu_f(z0), v.y * gv.y * silu_f(z1));
;       o.y = cvtpk(v.z * gv.z * silu_f(z2), v.w * gv.w * silu_f(z3));
;       *(uint2*)(mix + (row0 + rr) * 1024 + hh * 128 + cc * 4) = o;
;     }
	v_mul_f32_e32 v0, v0, v210
	v_mul_f32_e32 v4, 0xbfb8aa3b, v8
	v_exp_f32_e32 v4, v4
	v_mul_f32_e32 v1, v1, v211
	v_add_f32_e32 v4, 1.0, v4
	v_rcp_f32_e32 v4, v4
	s_nop 0
	v_mul_f32_e32 v4, v4, v8
	v_mul_f32_e32 v0, v4, v0
	v_mul_f32_e32 v4, 0xbfb8aa3b, v9
	v_exp_f32_e32 v4, v4
	v_lshlrev_b32_e32 v8, 16, v178
	v_add_f32_e32 v4, 1.0, v4
	v_rcp_f32_e32 v4, v4
	s_nop 0
	v_mul_f32_e32 v4, v4, v9
	v_mul_f32_e32 v1, v4, v1
	v_cvt_pk_bf16_f32 v0, v0, v1
	v_mul_f32_e32 v1, v2, v212
	v_mul_f32_e32 v2, 0xbfb8aa3b, v10
	v_exp_f32_e32 v2, v2
	v_and_b32_e32 v9, 0xffff0000, v178
	v_add_f32_e32 v2, 1.0, v2
	v_rcp_f32_e32 v2, v2
	s_nop 0
	v_mul_f32_e32 v2, v2, v10
	v_mul_f32_e32 v1, v2, v1
	v_mul_f32_e32 v2, v3, v213
	v_mul_f32_e32 v3, 0xbfb8aa3b, v11
	v_exp_f32_e32 v3, v3
	v_lshlrev_b32_e32 v10, 16, v179
	v_add_f32_e32 v3, 1.0, v3
	v_rcp_f32_e32 v3, v3
	s_nop 0
	v_mul_f32_e32 v3, v3, v11
	v_mul_f32_e32 v2, v3, v2
	v_cvt_pk_bf16_f32 v1, v1, v2
	v_lshlrev_b64 v[2:3], 11, v[176:177]
	v_lshl_add_u64 v[2:3], v[86:87], 0, v[2:3]
	global_store_dwordx2 v[2:3], v[0:1], off
	ds_read_b128 v[0:3], v89 offset:3168
	v_and_b32_e32 v11, 0xffff0000, v179
	s_waitcnt lgkmcnt(0)
	v_mul_f32_e32 v0, v0, v210
	v_mul_f32_e32 v4, 0xbfb8aa3b, v8
	v_exp_f32_e32 v4, v4
	v_mul_f32_e32 v1, v1, v211
	v_add_f32_e32 v4, 1.0, v4
	v_rcp_f32_e32 v4, v4
	s_nop 0
	v_mul_f32_e32 v4, v4, v8
	v_mul_f32_e32 v0, v4, v0
	v_mul_f32_e32 v4, 0xbfb8aa3b, v9
	v_exp_f32_e32 v4, v4
	v_lshlrev_b32_e32 v8, 16, v174
	v_add_f32_e32 v4, 1.0, v4
	v_rcp_f32_e32 v4, v4
	s_nop 0
	v_mul_f32_e32 v4, v4, v9
	v_mul_f32_e32 v1, v4, v1
	v_cvt_pk_bf16_f32 v0, v0, v1
	v_mul_f32_e32 v1, v2, v212
	v_mul_f32_e32 v2, 0xbfb8aa3b, v10
	v_exp_f32_e32 v2, v2
	v_and_b32_e32 v9, 0xffff0000, v174
	v_add_f32_e32 v2, 1.0, v2
	v_rcp_f32_e32 v2, v2
	s_nop 0
	v_mul_f32_e32 v2, v2, v10
	v_mul_f32_e32 v1, v2, v1
	v_mul_f32_e32 v2, v3, v213
	v_mul_f32_e32 v3, 0xbfb8aa3b, v11
	v_exp_f32_e32 v3, v3
	v_lshlrev_b32_e32 v10, 16, v175
	v_add_f32_e32 v3, 1.0, v3
	v_rcp_f32_e32 v3, v3
	s_nop 0
	v_mul_f32_e32 v3, v3, v11
	v_mul_f32_e32 v2, v3, v2
	v_cvt_pk_bf16_f32 v1, v1, v2
	v_lshlrev_b64 v[2:3], 11, v[172:173]
	v_lshl_add_u64 v[2:3], v[86:87], 0, v[2:3]
	global_store_dwordx2 v[2:3], v[0:1], off
	ds_read_b128 v[0:3], v89 offset:4224
	v_and_b32_e32 v11, 0xffff0000, v175
	s_waitcnt lgkmcnt(0)
	v_mul_f32_e32 v0, v0, v210
	v_mul_f32_e32 v4, 0xbfb8aa3b, v8
	v_exp_f32_e32 v4, v4
	v_mul_f32_e32 v1, v1, v211
	v_add_f32_e32 v4, 1.0, v4
	v_rcp_f32_e32 v4, v4
	s_nop 0
	v_mul_f32_e32 v4, v4, v8
	v_mul_f32_e32 v0, v4, v0
	v_mul_f32_e32 v4, 0xbfb8aa3b, v9
	v_exp_f32_e32 v4, v4
	v_lshlrev_b32_e32 v8, 16, v170
	v_add_f32_e32 v4, 1.0, v4
	v_rcp_f32_e32 v4, v4
	s_nop 0
	v_mul_f32_e32 v4, v4, v9
	v_mul_f32_e32 v1, v4, v1
	v_cvt_pk_bf16_f32 v0, v0, v1
	v_mul_f32_e32 v1, v2, v212
	v_mul_f32_e32 v2, 0xbfb8aa3b, v10
	v_exp_f32_e32 v2, v2
	v_and_b32_e32 v9, 0xffff0000, v170
	v_add_f32_e32 v2, 1.0, v2
	v_rcp_f32_e32 v2, v2
	s_nop 0
	v_mul_f32_e32 v2, v2, v10
	v_mul_f32_e32 v1, v2, v1
	v_mul_f32_e32 v2, v3, v213
	v_mul_f32_e32 v3, 0xbfb8aa3b, v11
	v_exp_f32_e32 v3, v3
	v_lshlrev_b32_e32 v10, 16, v171
	v_add_f32_e32 v3, 1.0, v3
	v_rcp_f32_e32 v3, v3
	s_nop 0
	v_mul_f32_e32 v3, v3, v11
	v_mul_f32_e32 v2, v3, v2
	v_cvt_pk_bf16_f32 v1, v1, v2
	v_lshlrev_b64 v[2:3], 11, v[168:169]
	v_lshl_add_u64 v[2:3], v[86:87], 0, v[2:3]
	global_store_dwordx2 v[2:3], v[0:1], off
	ds_read_b128 v[0:3], v89 offset:5280
	v_and_b32_e32 v11, 0xffff0000, v171
	s_waitcnt lgkmcnt(0)
	v_mul_f32_e32 v0, v0, v210
	v_mul_f32_e32 v4, 0xbfb8aa3b, v8
	v_exp_f32_e32 v4, v4
	v_mul_f32_e32 v1, v1, v211
	v_add_f32_e32 v4, 1.0, v4
	v_rcp_f32_e32 v4, v4
	s_nop 0
	v_mul_f32_e32 v4, v4, v8
	v_mul_f32_e32 v0, v4, v0
	v_mul_f32_e32 v4, 0xbfb8aa3b, v9
	v_exp_f32_e32 v4, v4
	v_lshlrev_b32_e32 v8, 16, v166
	v_add_f32_e32 v4, 1.0, v4
	v_rcp_f32_e32 v4, v4
	s_nop 0
	v_mul_f32_e32 v4, v4, v9
	v_mul_f32_e32 v1, v4, v1
	v_cvt_pk_bf16_f32 v0, v0, v1
	v_mul_f32_e32 v1, v2, v212
	v_mul_f32_e32 v2, 0xbfb8aa3b, v10
	v_exp_f32_e32 v2, v2
	v_and_b32_e32 v9, 0xffff0000, v166
	v_add_f32_e32 v2, 1.0, v2
	v_rcp_f32_e32 v2, v2
	s_nop 0
	v_mul_f32_e32 v2, v2, v10
	v_mul_f32_e32 v1, v2, v1
	v_mul_f32_e32 v2, v3, v213
	v_mul_f32_e32 v3, 0xbfb8aa3b, v11
	v_exp_f32_e32 v3, v3
	v_lshlrev_b32_e32 v10, 16, v167
	v_add_f32_e32 v3, 1.0, v3
	v_rcp_f32_e32 v3, v3
	s_nop 0
	v_mul_f32_e32 v3, v3, v11
	v_mul_f32_e32 v2, v3, v2
	v_cvt_pk_bf16_f32 v1, v1, v2
	v_lshlrev_b64 v[2:3], 11, v[164:165]
	v_lshl_add_u64 v[2:3], v[86:87], 0, v[2:3]
	global_store_dwordx2 v[2:3], v[0:1], off
	ds_read_b128 v[0:3], v91 offset:1056
	v_and_b32_e32 v11, 0xffff0000, v167
	s_waitcnt lgkmcnt(0)
	v_mul_f32_e32 v0, v0, v210
	v_mul_f32_e32 v4, 0xbfb8aa3b, v8
	v_exp_f32_e32 v4, v4
	v_mul_f32_e32 v1, v1, v211
	v_add_f32_e32 v4, 1.0, v4
	v_rcp_f32_e32 v4, v4
	s_nop 0
	v_mul_f32_e32 v4, v4, v8
	v_mul_f32_e32 v0, v4, v0
	v_mul_f32_e32 v4, 0xbfb8aa3b, v9
	v_exp_f32_e32 v4, v4
	v_lshlrev_b32_e32 v8, 16, v162
	v_add_f32_e32 v4, 1.0, v4
	v_rcp_f32_e32 v4, v4
	s_nop 0
	v_mul_f32_e32 v4, v4, v9
	v_mul_f32_e32 v1, v4, v1
	v_cvt_pk_bf16_f32 v0, v0, v1
	v_mul_f32_e32 v1, v2, v212
	v_mul_f32_e32 v2, 0xbfb8aa3b, v10
	v_exp_f32_e32 v2, v2
	v_and_b32_e32 v9, 0xffff0000, v162
	v_add_f32_e32 v2, 1.0, v2
	v_rcp_f32_e32 v2, v2
	s_nop 0
	v_mul_f32_e32 v2, v2, v10
	v_mul_f32_e32 v1, v2, v1
	v_mul_f32_e32 v2, v3, v213
	v_mul_f32_e32 v3, 0xbfb8aa3b, v11
	v_exp_f32_e32 v3, v3
	v_lshlrev_b32_e32 v10, 16, v163
	v_add_f32_e32 v3, 1.0, v3
	v_rcp_f32_e32 v3, v3
	s_nop 0
	v_mul_f32_e32 v3, v3, v11
	v_mul_f32_e32 v2, v3, v2
	v_cvt_pk_bf16_f32 v1, v1, v2
	v_lshlrev_b64 v[2:3], 11, v[160:161]
	v_lshl_add_u64 v[2:3], v[86:87], 0, v[2:3]
	global_store_dwordx2 v[2:3], v[0:1], off
	ds_read_b128 v[0:3], v91 offset:2112
	v_and_b32_e32 v11, 0xffff0000, v163
	s_waitcnt lgkmcnt(0)
; DI float bf2f(unsigned u) { return __uint_as_float(u << 16); }
; DI unsigned cvtpk(float lo, float hi) { f32x2_t v = {lo, hi}; bf16x2_t r = __builtin_convertvector(v, bf16x2_t); return __builtin_bit_cast(unsigned, r); }
; DI float silu_f(float x) { return x * __builtin_amdgcn_rcpf(1.f + __expf(-x)); }
; DI void phase_ogla(const Params& p, char* lds, int l) {
;     ...
; #pragma unroll
;     for (int it2 = 0; it2 < 16; ++it2) {
;       const int id = it2 * 64 + lane, rr = id >> 5, cc = id & 31;
;       const float4 v = *(const float4*)(stg + rr * 528 + cc * 16);
;       const uint2 zr = zq[it2];
;       const float4 gv = *(const float4*)(gg + cc * 4);
;       const float z0 = bf2f(zr.x & 0xffffu), z1 = __uint_as_float(zr.x & 0xffff0000u), z2 = bf2f(zr.y & 0xffffu), z3 = __uint_as_float(zr.y & 0xffff0000u);
;       uint2 o;
;       o.x = cvtpk(v.x * gv.x * silu_f(z0), v.y * gv.y * silu_f(z1));
;       o.y = cvtpk(v.z * gv.z * silu_f(z2), v.w * gv.w * silu_f(z3));
;       *(uint2*)(mix + (row0 + rr) * 1024 + hh * 128 + cc * 4) = o;
;     }
	v_mul_f32_e32 v0, v0, v210
	v_mul_f32_e32 v4, 0xbfb8aa3b, v8
	v_exp_f32_e32 v4, v4
	v_mul_f32_e32 v1, v1, v211
	v_add_f32_e32 v4, 1.0, v4
	v_rcp_f32_e32 v4, v4
	s_nop 0
	v_mul_f32_e32 v4, v4, v8
	v_mul_f32_e32 v0, v4, v0
	v_mul_f32_e32 v4, 0xbfb8aa3b, v9
	v_exp_f32_e32 v4, v4
	v_lshlrev_b32_e32 v8, 16, v158
	v_add_f32_e32 v4, 1.0, v4
	v_rcp_f32_e32 v4, v4
	s_nop 0
	v_mul_f32_e32 v4, v4, v9
	v_mul_f32_e32 v1, v4, v1
	v_cvt_pk_bf16_f32 v0, v0, v1
	v_mul_f32_e32 v1, v2, v212
	v_mul_f32_e32 v2, 0xbfb8aa3b, v10
	v_exp_f32_e32 v2, v2
	v_and_b32_e32 v9, 0xffff0000, v158
	v_add_f32_e32 v2, 1.0, v2
	v_rcp_f32_e32 v2, v2
	s_nop 0
	v_mul_f32_e32 v2, v2, v10
	v_mul_f32_e32 v1, v2, v1
	v_mul_f32_e32 v2, v3, v213
	v_mul_f32_e32 v3, 0xbfb8aa3b, v11
	v_exp_f32_e32 v3, v3
	v_lshlrev_b32_e32 v10, 16, v159
	v_add_f32_e32 v3, 1.0, v3
	v_rcp_f32_e32 v3, v3
	s_nop 0
	v_mul_f32_e32 v3, v3, v11
	v_mul_f32_e32 v2, v3, v2
	v_cvt_pk_bf16_f32 v1, v1, v2
	v_lshlrev_b64 v[2:3], 11, v[156:157]
	v_lshl_add_u64 v[2:3], v[86:87], 0, v[2:3]
	global_store_dwordx2 v[2:3], v[0:1], off
	ds_read_b128 v[0:3], v91 offset:3168
	v_and_b32_e32 v11, 0xffff0000, v159
	s_waitcnt lgkmcnt(0)
	v_mul_f32_e32 v0, v0, v210
	v_mul_f32_e32 v4, 0xbfb8aa3b, v8
	v_exp_f32_e32 v4, v4
	v_mul_f32_e32 v1, v1, v211
	v_add_f32_e32 v4, 1.0, v4
	v_rcp_f32_e32 v4, v4
	s_nop 0
	v_mul_f32_e32 v4, v4, v8
	v_mul_f32_e32 v0, v4, v0
	v_mul_f32_e32 v4, 0xbfb8aa3b, v9
	v_exp_f32_e32 v4, v4
	v_lshlrev_b32_e32 v8, 16, v152
	v_add_f32_e32 v4, 1.0, v4
	v_rcp_f32_e32 v4, v4
	s_nop 0
	v_mul_f32_e32 v4, v4, v9
	v_mul_f32_e32 v1, v4, v1
	v_cvt_pk_bf16_f32 v0, v0, v1
	v_mul_f32_e32 v1, v2, v212
	v_mul_f32_e32 v2, 0xbfb8aa3b, v10
	v_exp_f32_e32 v2, v2
	v_and_b32_e32 v9, 0xffff0000, v152
	v_add_f32_e32 v2, 1.0, v2
	v_rcp_f32_e32 v2, v2
	s_nop 0
	v_mul_f32_e32 v2, v2, v10
	v_mul_f32_e32 v1, v2, v1
	v_mul_f32_e32 v2, v3, v213
	v_mul_f32_e32 v3, 0xbfb8aa3b, v11
	v_exp_f32_e32 v3, v3
	v_lshlrev_b32_e32 v10, 16, v153
	v_add_f32_e32 v3, 1.0, v3
	v_rcp_f32_e32 v3, v3
	s_nop 0
	v_mul_f32_e32 v3, v3, v11
	v_mul_f32_e32 v2, v3, v2
	v_cvt_pk_bf16_f32 v1, v1, v2
	v_lshlrev_b64 v[2:3], 11, v[154:155]
	v_lshl_add_u64 v[2:3], v[86:87], 0, v[2:3]
	global_store_dwordx2 v[2:3], v[0:1], off
	ds_read_b128 v[0:3], v91 offset:4224
	v_and_b32_e32 v11, 0xffff0000, v153
	s_waitcnt lgkmcnt(0)
	v_mul_f32_e32 v0, v0, v210
	v_mul_f32_e32 v4, 0xbfb8aa3b, v8
	v_exp_f32_e32 v4, v4
	v_mul_f32_e32 v1, v1, v211
	v_add_f32_e32 v4, 1.0, v4
	v_rcp_f32_e32 v4, v4
	s_nop 0
	v_mul_f32_e32 v4, v4, v8
	v_mul_f32_e32 v0, v4, v0
	v_mul_f32_e32 v4, 0xbfb8aa3b, v9
	v_exp_f32_e32 v4, v4
	v_lshlrev_b32_e32 v8, 16, v148
	v_add_f32_e32 v4, 1.0, v4
	v_rcp_f32_e32 v4, v4
	s_nop 0
	v_mul_f32_e32 v4, v4, v9
	v_mul_f32_e32 v1, v4, v1
	v_cvt_pk_bf16_f32 v0, v0, v1
	v_mul_f32_e32 v1, v2, v212
	v_mul_f32_e32 v2, 0xbfb8aa3b, v10
	v_exp_f32_e32 v2, v2
	v_and_b32_e32 v9, 0xffff0000, v148
	v_add_f32_e32 v2, 1.0, v2
	v_rcp_f32_e32 v2, v2
	s_nop 0
	v_mul_f32_e32 v2, v2, v10
	v_mul_f32_e32 v1, v2, v1
	v_mul_f32_e32 v2, v3, v213
	v_mul_f32_e32 v3, 0xbfb8aa3b, v11
	v_exp_f32_e32 v3, v3
	v_lshlrev_b32_e32 v10, 16, v149
	v_add_f32_e32 v3, 1.0, v3
	v_rcp_f32_e32 v3, v3
	s_nop 0
	v_mul_f32_e32 v3, v3, v11
	v_mul_f32_e32 v2, v3, v2
	v_cvt_pk_bf16_f32 v1, v1, v2
	v_lshlrev_b64 v[2:3], 11, v[150:151]
	v_lshl_add_u64 v[2:3], v[86:87], 0, v[2:3]
	global_store_dwordx2 v[2:3], v[0:1], off
	ds_read_b128 v[0:3], v91 offset:5280
	v_and_b32_e32 v11, 0xffff0000, v149
	s_waitcnt lgkmcnt(0)
	v_mul_f32_e32 v0, v0, v210
	v_mul_f32_e32 v4, 0xbfb8aa3b, v8
	v_exp_f32_e32 v4, v4
	v_mul_f32_e32 v1, v1, v211
	v_add_f32_e32 v4, 1.0, v4
	v_rcp_f32_e32 v4, v4
	s_nop 0
	v_mul_f32_e32 v4, v4, v8
	v_mul_f32_e32 v0, v4, v0
	v_mul_f32_e32 v4, 0xbfb8aa3b, v9
	v_exp_f32_e32 v4, v4
	v_lshlrev_b32_e32 v8, 16, v144
	v_add_f32_e32 v4, 1.0, v4
	v_rcp_f32_e32 v4, v4
	s_nop 0
	v_mul_f32_e32 v4, v4, v9
	v_mul_f32_e32 v1, v4, v1
	v_cvt_pk_bf16_f32 v0, v0, v1
	v_mul_f32_e32 v1, v2, v212
	v_mul_f32_e32 v2, 0xbfb8aa3b, v10
	v_exp_f32_e32 v2, v2
	v_and_b32_e32 v9, 0xffff0000, v144
	v_add_f32_e32 v2, 1.0, v2
	v_rcp_f32_e32 v2, v2
	s_nop 0
	v_mul_f32_e32 v2, v2, v10
	v_mul_f32_e32 v1, v2, v1
	v_mul_f32_e32 v2, v3, v213
	v_mul_f32_e32 v3, 0xbfb8aa3b, v11
	v_exp_f32_e32 v3, v3
	v_lshlrev_b32_e32 v10, 16, v145
	v_add_f32_e32 v3, 1.0, v3
	v_rcp_f32_e32 v3, v3
	s_nop 0
	v_mul_f32_e32 v3, v3, v11
	v_mul_f32_e32 v2, v3, v2
	v_cvt_pk_bf16_f32 v1, v1, v2
	v_lshlrev_b64 v[2:3], 11, v[146:147]
	v_lshl_add_u64 v[2:3], v[86:87], 0, v[2:3]
	global_store_dwordx2 v[2:3], v[0:1], off
	ds_read_b128 v[0:3], v91 offset:6336
	v_and_b32_e32 v11, 0xffff0000, v145
	s_waitcnt lgkmcnt(0)
; DI float bf2f(unsigned u) { return __uint_as_float(u << 16); }
; DI unsigned cvtpk(float lo, float hi) { f32x2_t v = {lo, hi}; bf16x2_t r = __builtin_convertvector(v, bf16x2_t); return __builtin_bit_cast(unsigned, r); }
; DI float silu_f(float x) { return x * __builtin_amdgcn_rcpf(1.f + __expf(-x)); }
; DI void phase_ogla(const Params& p, char* lds, int l) {
;     ...
; #pragma unroll
;     for (int it2 = 0; it2 < 16; ++it2) {
;       const int id = it2 * 64 + lane, rr = id >> 5, cc = id & 31;
;       const float4 v = *(const float4*)(stg + rr * 528 + cc * 16);
;       const uint2 zr = zq[it2];
;       const float4 gv = *(const float4*)(gg + cc * 4);
;       const float z0 = bf2f(zr.x & 0xffffu), z1 = __uint_as_float(zr.x & 0xffff0000u), z2 = bf2f(zr.y & 0xffffu), z3 = __uint_as_float(zr.y & 0xffff0000u);
;       uint2 o;
;       o.x = cvtpk(v.x * gv.x * silu_f(z0), v.y * gv.y * silu_f(z1));
;       o.y = cvtpk(v.z * gv.z * silu_f(z2), v.w * gv.w * silu_f(z3));
;       *(uint2*)(mix + (row0 + rr) * 1024 + hh * 128 + cc * 4) = o;
;     }
;   }
	v_mul_f32_e32 v0, v0, v210
	v_mul_f32_e32 v4, 0xbfb8aa3b, v8
	v_exp_f32_e32 v4, v4
	v_mul_f32_e32 v1, v1, v211
	v_add_f32_e32 v4, 1.0, v4
	v_rcp_f32_e32 v4, v4
	s_nop 0
	v_mul_f32_e32 v4, v4, v8
	v_mul_f32_e32 v0, v4, v0
	v_mul_f32_e32 v4, 0xbfb8aa3b, v9
	v_exp_f32_e32 v4, v4
	v_lshlrev_b32_e32 v8, 16, v140
	v_add_f32_e32 v4, 1.0, v4
	v_rcp_f32_e32 v4, v4
	s_nop 0
	v_mul_f32_e32 v4, v4, v9
	v_mul_f32_e32 v1, v4, v1
	v_cvt_pk_bf16_f32 v0, v0, v1
	v_mul_f32_e32 v1, v2, v212
	v_mul_f32_e32 v2, 0xbfb8aa3b, v10
	v_exp_f32_e32 v2, v2
	v_and_b32_e32 v9, 0xffff0000, v140
	v_add_f32_e32 v2, 1.0, v2
	v_rcp_f32_e32 v2, v2
	s_nop 0
	v_mul_f32_e32 v2, v2, v10
	v_mul_f32_e32 v1, v2, v1
	v_mul_f32_e32 v2, v3, v213
	v_mul_f32_e32 v3, 0xbfb8aa3b, v11
	v_exp_f32_e32 v3, v3
	v_lshlrev_b32_e32 v10, 16, v141
	v_add_f32_e32 v3, 1.0, v3
	v_rcp_f32_e32 v3, v3
	s_nop 0
	v_mul_f32_e32 v3, v3, v11
	v_mul_f32_e32 v2, v3, v2
	v_cvt_pk_bf16_f32 v1, v1, v2
	v_lshlrev_b64 v[2:3], 11, v[142:143]
	v_lshl_add_u64 v[2:3], v[86:87], 0, v[2:3]
	global_store_dwordx2 v[2:3], v[0:1], off
	ds_read_b128 v[0:3], v91 offset:7392
	v_and_b32_e32 v11, 0xffff0000, v141
	s_waitcnt lgkmcnt(0)
	v_mul_f32_e32 v0, v0, v210
	v_mul_f32_e32 v4, 0xbfb8aa3b, v8
	v_exp_f32_e32 v4, v4
	v_mul_f32_e32 v1, v1, v211
	v_add_f32_e32 v4, 1.0, v4
	v_rcp_f32_e32 v4, v4
	s_nop 0
	v_mul_f32_e32 v4, v4, v8
	v_mul_f32_e32 v0, v4, v0
	v_mul_f32_e32 v4, 0xbfb8aa3b, v9
	v_exp_f32_e32 v4, v4
	v_lshlrev_b32_e32 v8, 16, v136
	v_add_f32_e32 v4, 1.0, v4
	v_rcp_f32_e32 v4, v4
	s_nop 0
	v_mul_f32_e32 v4, v4, v9
	v_mul_f32_e32 v1, v4, v1
	v_cvt_pk_bf16_f32 v0, v0, v1
	v_mul_f32_e32 v1, v2, v212
	v_mul_f32_e32 v2, 0xbfb8aa3b, v10
	v_exp_f32_e32 v2, v2
	v_and_b32_e32 v9, 0xffff0000, v136
	v_add_f32_e32 v2, 1.0, v2
	v_rcp_f32_e32 v2, v2
	s_nop 0
	v_mul_f32_e32 v2, v2, v10
	v_mul_f32_e32 v1, v2, v1
	v_mul_f32_e32 v2, v3, v213
	v_mul_f32_e32 v3, 0xbfb8aa3b, v11
	v_exp_f32_e32 v3, v3
	v_lshlrev_b32_e32 v10, 16, v137
	v_add_f32_e32 v3, 1.0, v3
	v_rcp_f32_e32 v3, v3
	s_nop 0
	v_mul_f32_e32 v3, v3, v11
	v_mul_f32_e32 v2, v3, v2
	v_cvt_pk_bf16_f32 v1, v1, v2
	v_lshlrev_b64 v[2:3], 11, v[138:139]
	v_lshl_add_u64 v[2:3], v[86:87], 0, v[2:3]
	global_store_dwordx2 v[2:3], v[0:1], off
	ds_read_b128 v[0:3], v91 offset:8448
	v_and_b32_e32 v11, 0xffff0000, v137
	s_waitcnt lgkmcnt(0)
	v_mul_f32_e32 v0, v0, v210
	v_mul_f32_e32 v4, 0xbfb8aa3b, v8
	v_exp_f32_e32 v4, v4
	v_mul_f32_e32 v1, v1, v211
	v_add_f32_e32 v4, 1.0, v4
	v_rcp_f32_e32 v4, v4
	s_nop 0
	v_mul_f32_e32 v4, v4, v8
	v_mul_f32_e32 v0, v4, v0
	v_mul_f32_e32 v4, 0xbfb8aa3b, v9
	v_exp_f32_e32 v4, v4
	v_lshlrev_b32_e32 v8, 16, v132
	v_add_f32_e32 v4, 1.0, v4
	v_rcp_f32_e32 v4, v4
	s_nop 0
	v_mul_f32_e32 v4, v4, v9
	v_mul_f32_e32 v1, v4, v1
	v_cvt_pk_bf16_f32 v0, v0, v1
	v_mul_f32_e32 v1, v2, v212
	v_mul_f32_e32 v2, 0xbfb8aa3b, v10
	v_exp_f32_e32 v2, v2
	v_and_b32_e32 v9, 0xffff0000, v132
	v_add_f32_e32 v2, 1.0, v2
	v_rcp_f32_e32 v2, v2
	s_nop 0
	v_mul_f32_e32 v2, v2, v10
	v_mul_f32_e32 v1, v2, v1
	v_mul_f32_e32 v2, v3, v213
	v_mul_f32_e32 v3, 0xbfb8aa3b, v11
	v_exp_f32_e32 v3, v3
	v_lshlrev_b32_e32 v10, 16, v133
	v_add_f32_e32 v3, 1.0, v3
	v_rcp_f32_e32 v3, v3
	s_nop 0
	v_mul_f32_e32 v3, v3, v11
	v_mul_f32_e32 v2, v3, v2
	v_cvt_pk_bf16_f32 v1, v1, v2
	v_lshlrev_b64 v[2:3], 11, v[134:135]
	v_lshl_add_u64 v[2:3], v[86:87], 0, v[2:3]
	global_store_dwordx2 v[2:3], v[0:1], off
	ds_read_b128 v[0:3], v91 offset:9504
	v_and_b32_e32 v11, 0xffff0000, v133
	s_waitcnt lgkmcnt(0)
	v_mul_f32_e32 v0, v0, v210
	v_mul_f32_e32 v4, 0xbfb8aa3b, v8
	v_exp_f32_e32 v4, v4
	v_mul_f32_e32 v1, v1, v211
	v_add_f32_e32 v4, 1.0, v4
	v_rcp_f32_e32 v4, v4
	s_nop 0
	v_mul_f32_e32 v4, v4, v8
	v_mul_f32_e32 v0, v4, v0
	v_mul_f32_e32 v4, 0xbfb8aa3b, v9
	v_exp_f32_e32 v4, v4
	v_lshlrev_b32_e32 v8, 16, v128
	v_add_f32_e32 v4, 1.0, v4
	v_rcp_f32_e32 v4, v4
	s_nop 0
	v_mul_f32_e32 v4, v4, v9
	v_mul_f32_e32 v1, v4, v1
	v_cvt_pk_bf16_f32 v0, v0, v1
	v_mul_f32_e32 v1, v2, v212
	v_mul_f32_e32 v2, 0xbfb8aa3b, v10
	v_exp_f32_e32 v2, v2
	v_and_b32_e32 v9, 0xffff0000, v128
	v_add_f32_e32 v2, 1.0, v2
	v_rcp_f32_e32 v2, v2
	s_nop 0
	v_mul_f32_e32 v2, v2, v10
	v_mul_f32_e32 v1, v2, v1
	v_mul_f32_e32 v2, v3, v213
	v_mul_f32_e32 v3, 0xbfb8aa3b, v11
	v_exp_f32_e32 v3, v3
	v_lshlrev_b32_e32 v10, 16, v129
	v_add_f32_e32 v3, 1.0, v3
	v_rcp_f32_e32 v3, v3
	s_nop 0
	v_mul_f32_e32 v3, v3, v11
	v_mul_f32_e32 v2, v3, v2
	v_cvt_pk_bf16_f32 v1, v1, v2
	v_lshlrev_b64 v[2:3], 11, v[130:131]
	v_lshl_add_u64 v[2:3], v[86:87], 0, v[2:3]
	global_store_dwordx2 v[2:3], v[0:1], off
	ds_read_b128 v[0:3], v91 offset:10560
	v_and_b32_e32 v11, 0xffff0000, v129
	s_waitcnt lgkmcnt(0)
	v_mul_f32_e32 v0, v0, v210
	v_mul_f32_e32 v4, 0xbfb8aa3b, v8
	v_exp_f32_e32 v4, v4
	v_mul_f32_e32 v1, v1, v211
	v_add_f32_e32 v4, 1.0, v4
	v_rcp_f32_e32 v4, v4
	s_nop 0
	v_mul_f32_e32 v4, v4, v8
	v_mul_f32_e32 v0, v4, v0
	v_mul_f32_e32 v4, 0xbfb8aa3b, v9
	v_exp_f32_e32 v4, v4
	s_nop 0
	v_add_f32_e32 v4, 1.0, v4
	v_rcp_f32_e32 v4, v4
	s_nop 0
	v_mul_f32_e32 v4, v4, v9
	v_mul_f32_e32 v1, v4, v1
	v_cvt_pk_bf16_f32 v0, v0, v1
	v_mul_f32_e32 v1, v2, v212
	v_mul_f32_e32 v2, 0xbfb8aa3b, v10
	v_exp_f32_e32 v2, v2
	s_nop 0
	v_add_f32_e32 v2, 1.0, v2
	v_rcp_f32_e32 v2, v2
	s_nop 0
	v_mul_f32_e32 v2, v2, v10
	v_mul_f32_e32 v1, v2, v1
	v_mul_f32_e32 v2, v3, v213
	v_mul_f32_e32 v3, 0xbfb8aa3b, v11
	v_exp_f32_e32 v3, v3
	s_nop 0
	v_add_f32_e32 v3, 1.0, v3
	v_rcp_f32_e32 v3, v3
	s_nop 0
	v_mul_f32_e32 v3, v3, v11
	v_mul_f32_e32 v2, v3, v2
	v_cvt_pk_bf16_f32 v1, v1, v2
	v_lshlrev_b64 v[2:3], 11, v[126:127]
	v_lshl_add_u64 v[2:3], v[86:87], 0, v[2:3]
	global_store_dwordx2 v[2:3], v[0:1], off
	s_cbranch_scc1 .LBB0_743
	s_mov_b64 s[72:73], s[24:25]
